# w_in GEMM: odd rounds take the neighbouring XCD's tile chunk so every workgroup gets a mix of cheap and costly epilogues
# speedup vs baseline: 1.0024x; 1.0024x over previous
.LBB0_131:
	s_add_i32 s29, s29, 1
	s_mul_i32 s4, s29, s42
	s_mul_hi_u32 s5, s29, s33
	s_add_i32 s5, s5, s4
	s_mul_i32 s4, s29, s33
	s_add_u32 s46, s4, s2
	s_addc_u32 s47, s5, s43
	v_cmp_gt_i64_e32 vcc, s[46:47], v[150:151]
	v_cmp_lt_i64_e64 s[56:57], s[46:47], v[148:149]
	s_cbranch_vccnz .LBB0_137
	s_ashr_i32 s7, s46, 31
	s_lshr_b32 s7, s7, 29
	s_add_i32 s7, s46, s7
	s_and_b32 s40, s7, -8
	s_sub_i32 s44, s46, s40
	s_bfe_u32 s40, s46, 0x10008
	s_xor_b32 s44, s44, s40
	s_cmp_gt_i32 s44, 5
	s_mov_b64 s[40:41], -1
	s_cbranch_scc0 .LBB0_134
	s_mul_i32 s40, s44, 0x7b
	s_add_i32 s45, s40, 6
	s_mov_b64 s[40:41], 0
